# S5 unit: the 8 LDS reads of the serial recurrence issued up front (counted lgkmcnt), on top of the SSD prompt unit changes
# baseline (speedup 1.0000x reference)
.LBB0_274:
	s_add_i32 s70, s71, 1
	s_lshr_b32 s26, s70, 2
	s_add_i32 s26, s26, s3
	s_lshl_b32 s26, s26, 8
	s_and_b32 s36, s69, 0xc0
	s_or_b32 s26, s26, s36
	s_cmp_eq_u32 s71, 7
	s_cselect_b32 s26, s68, s26
	s_lshl_b64 s[36:37], s[26:27], 8
	s_add_u32 s36, s66, s36
	v_add_u32_e32 v193, v172, v168
	v_add_u32_e32 v194, v172, v166
	s_addc_u32 s37, s67, s37
	s_waitcnt vmcnt(0)
	ds_write_b128 v193, v[50:53] offset:55296
	ds_write_b128 v194, v[54:57] offset:55296
	v_lshl_add_u64 v[50:51], s[36:37], 0, v[140:141]
	v_lshl_add_u64 v[54:55], s[36:37], 0, v[142:143]
	global_load_dwordx4 v[50:53], v[50:51], off
	s_nop 0
	global_load_dwordx4 v[54:57], v[54:55], off
	s_waitcnt lgkmcnt(0)
	s_barrier
	ds_read_b128 v[106:109], v171 offset:55296
	ds_read_b128 v[110:113], v171 offset:55360
	s_waitcnt lgkmcnt(1)
	v_mfma_f32_16x16x32_bf16 v[58:61], v[106:109], v[2:5], 0
	ds_read_b128 v[118:121], v171 offset:55424
	ds_read_b128 v[114:117], v171 offset:55488
	ds_read_b128 v[102:105], v171 offset:59648
	ds_read_b128 v[94:97], v171 offset:59712
	ds_read_b128 v[98:101], v171 offset:59776
	ds_read_b128 v[70:73], v170 offset:55296
	s_waitcnt lgkmcnt(6)
	v_mfma_f32_16x16x32_bf16 v[58:61], v[110:113], v[10:13], v[58:61]
	ds_read_b128 v[90:93], v171 offset:59840
	ds_read_b128 v[86:89], v171 offset:64000
	ds_read_b128 v[82:85], v171 offset:64064
	ds_read_b128 v[78:81], v171 offset:64128
	s_waitcnt lgkmcnt(9)
	v_mfma_f32_16x16x32_bf16 v[58:61], v[118:121], v[22:25], v[58:61]
	ds_read_b128 v[74:77], v171 offset:64192
	v_add_u32_e32 v195, 0x400, v169
	s_and_b32 s26, s71, 3
	s_waitcnt lgkmcnt(8)
	v_mfma_f32_16x16x32_bf16 v[62:65], v[102:105], v[2:5], 0
	s_cmp_eq_u32 s26, 0
	s_cselect_b64 s[36:37], -1, 0
	v_cndmask_b32_e64 v126, v147, 0, s[36:37]
	v_mfma_f32_16x16x32_bf16 v[196:199], v[114:117], v[34:37], v[58:61]
	s_cmp_eq_u32 s26, 3
	s_waitcnt lgkmcnt(7)
	v_mfma_f32_16x16x32_bf16 v[58:61], v[94:97], v[10:13], v[62:65]
	s_waitcnt lgkmcnt(6)
	v_mfma_f32_16x16x32_bf16 v[58:61], v[98:101], v[22:25], v[58:61]
	s_waitcnt lgkmcnt(4)
	v_mfma_f32_16x16x32_bf16 v[200:203], v[90:93], v[34:37], v[58:61]
	s_waitcnt lgkmcnt(3)
	v_mfma_f32_16x16x32_bf16 v[58:61], v[86:89], v[2:5], 0
	s_waitcnt lgkmcnt(2)
	v_mfma_f32_16x16x32_bf16 v[58:61], v[82:85], v[10:13], v[58:61]
	s_waitcnt lgkmcnt(1)
	v_mfma_f32_16x16x32_bf16 v[58:61], v[78:81], v[22:25], v[58:61]
	v_mfma_f32_16x16x32_bf16 v[208:211], v[70:73], v[2:5], 0
	s_waitcnt lgkmcnt(0)
	v_mfma_f32_16x16x32_bf16 v[204:207], v[74:77], v[34:37], v[58:61]
	ds_read_b128 v[66:69], v170 offset:55360
	ds_read_b128 v[62:65], v170 offset:55424
	s_nop 2
	ds_read_b128 v[58:61], v170 offset:55488
	ds_write2_b32 v169, v196, v197 offset1:132
	ds_write2_b32 v195, v198, v199 offset0:8 offset1:140
	s_waitcnt lgkmcnt(4)
	v_mfma_f32_16x16x32_bf16 v[208:211], v[66:69], v[10:13], v[208:211]
	v_add_u32_e32 v197, 0x2400, v169
	v_add_u32_e32 v198, 0x4200, v169
	ds_write2_b32 v197, v202, v203 offset0:72 offset1:204
	s_waitcnt lgkmcnt(4)
	v_mfma_f32_16x16x32_bf16 v[208:211], v[62:65], v[22:25], v[208:211]
	ds_write2_b32 v198, v204, v205 offset1:132
	v_add_u32_e32 v196, 0x2000, v169
	ds_write2_b32 v196, v200, v201 offset0:64 offset1:196
	s_waitcnt lgkmcnt(5)
	v_mfma_f32_16x16x32_bf16 v[202:205], v[58:61], v[34:37], v[208:211]
	v_add_u32_e32 v199, 0x4600, v169
	v_add_u32_e32 v200, 0x6200, v169
	v_add_u32_e32 v201, 0x6600, v169
	ds_write2_b32 v199, v206, v207 offset0:8 offset1:140
	v_cndmask_b32_e64 v208, v146, 0, s[36:37]
	s_nop 2
	ds_write2_b32 v200, v202, v203 offset0:64 offset1:196
	ds_write2_b32 v201, v204, v205 offset0:72 offset1:204
	s_waitcnt lgkmcnt(0)
	s_barrier
	ds_read2st64_b32 v[202:203], v175 offset1:1
	ds_read2st64_b32 v[204:205], v177 offset1:1
	ds_read2st64_b32 v[230:231], v178 offset1:1
	ds_read2st64_b32 v[232:233], v179 offset1:1
	ds_read2st64_b32 v[234:235], v180 offset1:1
	ds_read2st64_b32 v[236:237], v181 offset1:1
	ds_read2st64_b32 v[238:239], v182 offset1:1
	ds_read2st64_b32 v[240:241], v183 offset1:1
	v_cndmask_b32_e64 v210, 0, v208, s[0:1]
	v_cndmask_b32_e64 v209, 0, v126, s[0:1]
	s_cselect_b64 s[36:37], -1, 0
	s_waitcnt lgkmcnt(7)
	v_add_f32_e32 v215, v150, v203
	v_add_f32_e32 v214, v176, v202
	v_mul_f32_e32 v147, v135, v215
	v_fma_f32 v147, v134, v214, -v147
	s_waitcnt lgkmcnt(6)
	v_add_f32_e32 v216, v204, v147
	v_mul_f32_e32 v147, v134, v215
	v_fmac_f32_e32 v147, v135, v214
	v_add_f32_e32 v217, v205, v147
	v_mul_f32_e32 v147, v135, v217
	v_fma_f32 v147, v134, v216, -v147
	s_waitcnt lgkmcnt(5)
	v_add_f32_e32 v218, v230, v147
	v_mul_f32_e32 v147, v135, v216
	v_fmac_f32_e32 v147, v134, v217
	v_add_f32_e32 v219, v231, v147
	v_mul_f32_e32 v147, v135, v219
	v_fma_f32 v147, v134, v218, -v147
	s_waitcnt lgkmcnt(4)
	v_add_f32_e32 v220, v232, v147
	v_mul_f32_e32 v147, v135, v218
	v_fmac_f32_e32 v147, v134, v219
	v_add_f32_e32 v221, v233, v147
	v_mul_f32_e32 v147, v135, v221
	v_fma_f32 v147, v134, v220, -v147
	s_waitcnt lgkmcnt(3)
	v_add_f32_e32 v222, v234, v147
	v_mul_f32_e32 v147, v135, v220
	v_fmac_f32_e32 v147, v134, v221
	v_add_f32_e32 v223, v235, v147
	v_mul_f32_e32 v147, v135, v223
	v_fma_f32 v147, v134, v222, -v147
	s_waitcnt lgkmcnt(2)
	v_add_f32_e32 v224, v236, v147
	v_mul_f32_e32 v147, v135, v222
	v_fmac_f32_e32 v147, v134, v223
	v_add_f32_e32 v225, v237, v147
	v_mul_f32_e32 v147, v135, v225
	v_fma_f32 v147, v134, v224, -v147
	s_waitcnt lgkmcnt(1)
	v_add_f32_e32 v226, v238, v147
	v_mul_f32_e32 v147, v135, v224
	v_fmac_f32_e32 v147, v134, v225
	v_add_f32_e32 v227, v239, v147
	v_mul_f32_e32 v147, v135, v227
	v_mul_f32_e32 v202, v135, v226
	v_fma_f32 v147, v134, v226, -v147
	v_fmac_f32_e32 v202, v134, v227
	s_waitcnt lgkmcnt(0)
	v_add_f32_e32 v147, v240, v147
	v_add_f32_e32 v202, v241, v202
	ds_write2st64_b32 v173, v147, v202 offset0:200 offset1:201
	s_waitcnt lgkmcnt(0)
	s_barrier
	ds_read2st64_b32 v[146:147], v184 offset0:200 offset1:201
	v_mul_f32_e32 v202, v136, v126
	v_fma_f32 v211, v144, v208, -v202
	v_mul_f32_e32 v208, v136, v208
	v_fmac_f32_e32 v208, v144, v126
	s_waitcnt lgkmcnt(0)
	v_add_f32_e32 v146, v211, v146
	v_add_f32_e32 v147, v208, v147
	ds_read2st64_b32 v[202:203], v184 offset0:202 offset1:203
	ds_read2st64_b32 v[204:205], v184 offset0:204 offset1:205
	ds_read2st64_b32 v[206:207], v184 offset0:206 offset1:207
	v_cndmask_b32_e64 v228, v210, v146, s[4:5]
	v_pk_mul_f32 v[210:211], v[136:137], v[146:147]
	v_cndmask_b32_e64 v126, v209, v147, s[4:5]
	v_pk_fma_f32 v[212:213], v[144:145], v[146:147], v[210:211] op_sel:[0,0,1] op_sel_hi:[1,1,0] neg_lo:[0,0,1] neg_hi:[0,0,1]
	v_pk_fma_f32 v[146:147], v[144:145], v[146:147], v[210:211] op_sel:[0,0,1] op_sel_hi:[1,1,0]
	ds_read2st64_b32 v[208:209], v184 offset0:208 offset1:209
	v_mov_b32_e32 v213, v147
	s_waitcnt lgkmcnt(3)
	v_pk_add_f32 v[146:147], v[202:203], v[212:213]
	s_and_b64 s[72:73], s[36:37], s[0:1]
	v_pk_mul_f32 v[202:203], v[136:137], v[146:147]
	v_cndmask_b32_e64 v126, v126, v147, s[6:7]
	v_cndmask_b32_e64 v212, v228, v146, s[6:7]
	v_pk_fma_f32 v[210:211], v[144:145], v[146:147], v[202:203] op_sel:[0,0,1] op_sel_hi:[1,1,0] neg_lo:[0,0,1] neg_hi:[0,0,1]
	v_pk_fma_f32 v[146:147], v[144:145], v[146:147], v[202:203] op_sel:[0,0,1] op_sel_hi:[1,1,0]
	s_mov_b64 s[36:37], -1
	v_mov_b32_e32 v211, v147
	s_waitcnt lgkmcnt(2)
	v_pk_add_f32 v[146:147], v[204:205], v[210:211]
	s_and_b64 vcc, exec, s[72:73]
	v_pk_mul_f32 v[202:203], v[136:137], v[146:147]
	v_cndmask_b32_e64 v126, v126, v147, s[8:9]
	v_cndmask_b32_e64 v210, v212, v146, s[8:9]
	v_pk_fma_f32 v[204:205], v[144:145], v[146:147], v[202:203] op_sel:[0,0,1] op_sel_hi:[1,1,0] neg_lo:[0,0,1] neg_hi:[0,0,1]
	v_pk_fma_f32 v[146:147], v[144:145], v[146:147], v[202:203] op_sel:[0,0,1] op_sel_hi:[1,1,0]
	s_nop 0
	v_mov_b32_e32 v205, v147
	s_waitcnt lgkmcnt(1)
	v_pk_add_f32 v[146:147], v[206:207], v[204:205]
	s_nop 0
	v_pk_mul_f32 v[202:203], v[136:137], v[146:147]
	v_cndmask_b32_e64 v126, v126, v147, s[10:11]
	v_cndmask_b32_e64 v210, v210, v146, s[10:11]
	v_pk_fma_f32 v[204:205], v[144:145], v[146:147], v[202:203] op_sel:[0,0,1] op_sel_hi:[1,1,0] neg_lo:[0,0,1] neg_hi:[0,0,1]
	v_pk_fma_f32 v[146:147], v[144:145], v[146:147], v[202:203] op_sel:[0,0,1] op_sel_hi:[1,1,0]
	s_nop 0
	v_mov_b32_e32 v205, v147
	s_waitcnt lgkmcnt(0)
	v_pk_add_f32 v[204:205], v[208:209], v[204:205]
	ds_read2st64_b32 v[146:147], v184 offset0:210 offset1:211
	ds_read2st64_b32 v[202:203], v184 offset0:212 offset1:213
	ds_read2st64_b32 v[206:207], v184 offset0:214 offset1:215
	v_pk_mul_f32 v[208:209], v[136:137], v[204:205]
	v_cndmask_b32_e64 v126, v126, v205, s[12:13]
	v_cndmask_b32_e64 v212, v210, v204, s[12:13]
	v_pk_fma_f32 v[210:211], v[144:145], v[204:205], v[208:209] op_sel:[0,0,1] op_sel_hi:[1,1,0] neg_lo:[0,0,1] neg_hi:[0,0,1]
	v_pk_fma_f32 v[204:205], v[144:145], v[204:205], v[208:209] op_sel:[0,0,1] op_sel_hi:[1,1,0]
	s_nop 0
	v_mov_b32_e32 v211, v205
	s_waitcnt lgkmcnt(2)
	v_pk_add_f32 v[146:147], v[146:147], v[210:211]
	s_nop 0
	v_pk_mul_f32 v[204:205], v[136:137], v[146:147]
	v_cndmask_b32_e64 v126, v126, v147, s[14:15]
	v_cndmask_b32_e64 v210, v212, v146, s[14:15]
	v_pk_fma_f32 v[208:209], v[144:145], v[146:147], v[204:205] op_sel:[0,0,1] op_sel_hi:[1,1,0] neg_lo:[0,0,1] neg_hi:[0,0,1]
	v_pk_fma_f32 v[146:147], v[144:145], v[146:147], v[204:205] op_sel:[0,0,1] op_sel_hi:[1,1,0]
	s_nop 0
	v_mov_b32_e32 v209, v147
	s_waitcnt lgkmcnt(1)
	v_pk_add_f32 v[146:147], v[202:203], v[208:209]
	s_nop 0
	v_pk_mul_f32 v[202:203], v[136:137], v[146:147]
	v_cndmask_b32_e64 v126, v126, v147, s[16:17]
	v_cndmask_b32_e64 v208, v210, v146, s[16:17]
	v_pk_fma_f32 v[204:205], v[144:145], v[146:147], v[202:203] op_sel:[0,0,1] op_sel_hi:[1,1,0] neg_lo:[0,0,1] neg_hi:[0,0,1]
	v_pk_fma_f32 v[146:147], v[144:145], v[146:147], v[202:203] op_sel:[0,0,1] op_sel_hi:[1,1,0]
	v_fmac_f32_e32 v214, v151, v208
	v_add_f32_e32 v146, 0, v208
	v_fmac_f32_e32 v146, 0x80000000, v126
	v_cvt_pk_bf16_f32 v146, v146, s0
	ds_write_b16 v185, v146 offset:33792
	v_add_f32_e32 v146, 0, v126
	v_fmac_f32_e32 v146, 0, v208
	v_cvt_pk_bf16_f32 v146, v146, s0
	ds_write_b16 v185, v146 offset:33920
	v_fma_f32 v146, -v152, v126, v214
	v_fmac_f32_e32 v215, v151, v126
	v_cvt_pk_bf16_f32 v146, v146, s0
	v_fmac_f32_e32 v215, v152, v208
	ds_write_b16 v186, v146 offset:33792
	v_cvt_pk_bf16_f32 v146, v215, s0
	v_fmac_f32_e32 v216, v153, v208
	ds_write_b16 v186, v146 offset:33920
	v_fma_f32 v146, -v154, v126, v216
	v_fmac_f32_e32 v217, v153, v126
	v_cvt_pk_bf16_f32 v146, v146, s0
	v_fmac_f32_e32 v217, v154, v208
	ds_write_b16 v187, v146 offset:33792
	v_cvt_pk_bf16_f32 v146, v217, s0
	v_fmac_f32_e32 v218, v155, v208
	ds_write_b16 v187, v146 offset:33920
	v_fma_f32 v146, -v156, v126, v218
	v_fmac_f32_e32 v219, v155, v126
	v_cvt_pk_bf16_f32 v146, v146, s0
	v_fmac_f32_e32 v219, v156, v208
	ds_write_b16 v188, v146 offset:33792
	v_cvt_pk_bf16_f32 v146, v219, s0
	v_fmac_f32_e32 v220, v157, v208
	ds_write_b16 v188, v146 offset:33920
	v_fma_f32 v146, -v158, v126, v220
	v_fmac_f32_e32 v221, v157, v126
	v_cvt_pk_bf16_f32 v146, v146, s0
	v_fmac_f32_e32 v221, v158, v208
	ds_write_b16 v189, v146 offset:33792
	v_cvt_pk_bf16_f32 v146, v221, s0
	v_fmac_f32_e32 v222, v159, v208
	ds_write_b16 v189, v146 offset:33920
	v_fma_f32 v146, -v160, v126, v222
	v_fmac_f32_e32 v223, v159, v126
	v_cvt_pk_bf16_f32 v146, v146, s0
	v_fmac_f32_e32 v223, v160, v208
	ds_write_b16 v190, v146 offset:33792
	v_cvt_pk_bf16_f32 v146, v223, s0
	v_fmac_f32_e32 v224, v161, v208
	ds_write_b16 v190, v146 offset:33920
	v_fma_f32 v146, -v162, v126, v224
	v_fmac_f32_e32 v225, v161, v126
	v_cvt_pk_bf16_f32 v146, v146, s0
	v_fmac_f32_e32 v225, v162, v208
	ds_write_b16 v191, v146 offset:33792
	v_cvt_pk_bf16_f32 v146, v225, s0
	v_fmac_f32_e32 v226, v163, v208
	ds_write_b16 v191, v146 offset:33920
	v_fma_f32 v146, -v164, v126, v226
	v_fmac_f32_e32 v227, v163, v126
	v_mov_b32_e32 v205, v147
	v_cvt_pk_bf16_f32 v146, v146, s0
	v_fmac_f32_e32 v227, v164, v208
	ds_write_b16 v192, v146 offset:33792
	v_cvt_pk_bf16_f32 v126, v227, s0
	s_waitcnt lgkmcnt(14)
	v_pk_add_f32 v[146:147], v[206:207], v[204:205]
	ds_write_b16 v192, v126 offset:33920
	s_cbranch_vccnz .LBB0_276
	s_mov_b64 s[36:37], 0
